# attention: waves 4-7 delayed by s_sleep 32 at the start of each round's compute section (SIMD partner stagger)
# speedup vs baseline: 1.0087x; 1.0036x over previous
.LBB0_446:
	s_cmp_lt_u32 s2, 4
	s_cbranch_scc1 .Lmy_at_go
	s_sleep 32
